# attention: 5-stage LDS K/V ring (tile written 3 steps ahead) so the workgroup barrier is needed only every second KV tile
# speedup vs baseline: 1.0060x; 1.0031x over previous
.LBB0_730:
	v_and_b32_e32 v33, 64, v187
	v_xor_b32_e32 v32, 32, v187
	v_add_u32_e32 v33, 64, v33
	v_cmp_lt_i32_e32 vcc, v32, v33
	v_mov_b32_e32 v161, v97
	s_add_i32 s36, s36, s72
	v_cndmask_b32_e32 v32, v187, v32, vcc
	v_lshlrev_b32_e32 v32, 2, v32
	ds_bpermute_b32 v32, v32, v157
	s_cmpk_lt_i32 s36, 0x400
	s_waitcnt lgkmcnt(0)
	v_add_f32_e32 v32, v157, v32
	v_div_scale_f32 v33, s[0:1], v32, v32, 1.0
	v_rcp_f32_e32 v34, v33
	v_div_scale_f32 v35, vcc, 1.0, v32, 1.0
	v_fma_f32 v36, -v33, v34, 1.0
	v_fmac_f32_e32 v34, v36, v34
	v_mul_f32_e32 v36, v35, v34
	v_fma_f32 v37, -v33, v36, v35
	v_fmac_f32_e32 v36, v37, v34
	v_fma_f32 v33, -v33, v36, v35
	v_div_fmas_f32 v33, v33, v34, v36
	v_div_fixup_f32 v32, v33, v32, 1.0
	v_mul_u32_u24_e32 v36, 0x90, v137
	v_add_u32_e32 v36, v36, v160
	v_add_u32_e32 v36, 0x1ae00, v36
	v_and_b32_e32 v38, 31, v187
	v_lshrrev_b32_e32 v39, 3, v187
	v_sub_u32_e32 v40, v39, v38
	v_add_u32_e32 v37, v137, v40
	v_mul_u32_u24_e32 v37, 0x90, v37
	v_and_b32_e32 v41, 7, v187
	v_lshlrev_b32_e32 v41, 4, v41
	v_add_u32_e32 v37, v37, v41
	v_add_u32_e32 v37, 0x1ae00, v37
	v_lshl_add_u32 v38, v40, 10, v41
	v_ashrrev_i32_e32 v39, 31, v38
	v_lshl_add_u64 v[34:35], v[166:167], 0, v[38:39]
	v_pk_mul_f32 v[0:1], v[0:1], v[32:33] op_sel_hi:[1,0]
	v_pk_mul_f32 v[2:3], v[2:3], v[32:33] op_sel_hi:[1,0]
	v_cvt_pk_bf16_f32 v0, v0, v1
	v_cvt_pk_bf16_f32 v1, v2, v3
	ds_write_b64 v36, v[0:1]
	v_pk_mul_f32 v[4:5], v[4:5], v[32:33] op_sel_hi:[1,0]
	v_pk_mul_f32 v[6:7], v[6:7], v[32:33] op_sel_hi:[1,0]
	v_cvt_pk_bf16_f32 v4, v4, v5
	v_cvt_pk_bf16_f32 v5, v6, v7
	ds_write_b64 v36, v[4:5] offset:16
	v_pk_mul_f32 v[8:9], v[8:9], v[32:33] op_sel_hi:[1,0]
	v_pk_mul_f32 v[10:11], v[10:11], v[32:33] op_sel_hi:[1,0]
	v_cvt_pk_bf16_f32 v8, v8, v9
	v_cvt_pk_bf16_f32 v9, v10, v11
	ds_write_b64 v36, v[8:9] offset:32
	v_pk_mul_f32 v[12:13], v[12:13], v[32:33] op_sel_hi:[1,0]
	v_pk_mul_f32 v[14:15], v[14:15], v[32:33] op_sel_hi:[1,0]
	v_cvt_pk_bf16_f32 v12, v12, v13
	v_cvt_pk_bf16_f32 v13, v14, v15
	ds_write_b64 v36, v[12:13] offset:48
	v_pk_mul_f32 v[16:17], v[16:17], v[32:33] op_sel_hi:[1,0]
	v_pk_mul_f32 v[18:19], v[18:19], v[32:33] op_sel_hi:[1,0]
	v_cvt_pk_bf16_f32 v16, v16, v17
	v_cvt_pk_bf16_f32 v17, v18, v19
	ds_write_b64 v36, v[16:17] offset:64
	v_pk_mul_f32 v[20:21], v[20:21], v[32:33] op_sel_hi:[1,0]
	v_pk_mul_f32 v[22:23], v[22:23], v[32:33] op_sel_hi:[1,0]
	v_cvt_pk_bf16_f32 v20, v20, v21
	v_cvt_pk_bf16_f32 v21, v22, v23
	ds_write_b64 v36, v[20:21] offset:80
	v_pk_mul_f32 v[24:25], v[24:25], v[32:33] op_sel_hi:[1,0]
	v_pk_mul_f32 v[26:27], v[26:27], v[32:33] op_sel_hi:[1,0]
	v_cvt_pk_bf16_f32 v24, v24, v25
	v_cvt_pk_bf16_f32 v25, v26, v27
	ds_write_b64 v36, v[24:25] offset:96
	v_pk_mul_f32 v[28:29], v[28:29], v[32:33] op_sel_hi:[1,0]
	v_pk_mul_f32 v[30:31], v[30:31], v[32:33] op_sel_hi:[1,0]
	v_cvt_pk_bf16_f32 v28, v28, v29
	v_cvt_pk_bf16_f32 v29, v30, v31
	ds_write_b64 v36, v[28:29] offset:112
	s_waitcnt lgkmcnt(0)
	ds_read_b128 v[0:3], v37
	ds_read_b128 v[4:7], v37 offset:1152
	ds_read_b128 v[8:11], v37 offset:2304
	ds_read_b128 v[12:15], v37 offset:3456
	s_mov_b64 s[8:9], 0x2000
	s_waitcnt lgkmcnt(3)
	global_store_dwordx4 v[34:35], v[0:3], off
	v_lshl_add_u64 v[34:35], v[34:35], 0, s[8:9]
	s_waitcnt lgkmcnt(2)
	global_store_dwordx4 v[34:35], v[4:7], off
	v_lshl_add_u64 v[34:35], v[34:35], 0, s[8:9]
	s_waitcnt lgkmcnt(1)
	global_store_dwordx4 v[34:35], v[8:11], off
	v_lshl_add_u64 v[34:35], v[34:35], 0, s[8:9]
	s_waitcnt lgkmcnt(0)
	global_store_dwordx4 v[34:35], v[12:15], off
	s_cbranch_scc0 .LBB0_762
.LBB0_731:
	s_ashr_i32 s0, s36, 4
	s_ashr_i32 s6, s36, 7
	s_and_b32 s10, s0, 7
	s_mul_hi_i32 s1, s0, 0x88000
	s_mul_i32 s0, s0, 0x88000
	s_add_u32 s4, s37, s0
	s_addc_u32 s5, s38, s1
	s_ashr_i32 s7, s6, 31
	s_lshl_b64 s[8:9], s[6:7], 12
	s_lshl_b32 s7, s36, 8
	s_and_b32 s7, s7, 0xf00
	v_add_u32_e32 v96, s7, v137
	v_lshl_add_u64 v[0:1], s[8:9], 0, v[96:97]
	v_lshlrev_b64 v[2:3], 10, v[0:1]
	v_lshlrev_b64 v[0:1], 9, v[0:1]
	s_lshl_b32 s24, s10, 6
	v_lshl_add_u64 v[0:1], s[54:55], 0, v[0:1]
	v_lshl_add_u64 v[0:1], v[0:1], 0, s[24:25]
	v_lshl_add_u64 v[2:3], s[22:23], 0, v[2:3]
	s_lshl_b32 s8, s10, 7
	s_mov_b32 s9, s25
	v_lshl_add_u64 v[0:1], v[0:1], 0, v[162:163]
	v_lshl_add_u64 v[166:167], v[2:3], 0, s[8:9]
	v_add_co_u32_e32 v0, vcc, 0x4400000, v0
	v_lshl_add_u64 v[2:3], v[166:167], 0, v[162:163]
	s_nop 0
	v_addc_co_u32_e32 v1, vcc, 0, v1, vcc
	global_load_dwordx4 v[100:103], v[2:3], off
	global_load_dwordx4 v[104:107], v[2:3], off offset:32
	global_load_dwordx4 v[108:111], v[2:3], off offset:64
	global_load_dwordx4 v[112:115], v[2:3], off offset:96
	global_load_dwordx4 v[116:119], v[0:1], off
	global_load_dwordx4 v[120:123], v[0:1], off offset:32
	s_mul_i32 s34, s6, 0x44000
	s_mul_hi_i32 s35, s6, 0x44000
	s_add_u32 s6, s39, s34
	s_addc_u32 s7, s40, s35
	global_load_dwordx4 v[188:191], v154, s[4:5]
	s_add_u32 s12, s4, 0x2000
	s_addc_u32 s13, s5, 0
	global_load_dwordx4 v[128:131], v154, s[12:13]
	v_and_b32_e32 v196, 0xfff, v152
	global_load_dwordx4 v[124:127], v196, s[6:7]
	s_add_u32 s12, s6, 0x1000
	s_addc_u32 s13, s7, 0
	global_load_dwordx4 v[192:195], v196, s[12:13]
	v_lshl_add_u64 v[12:13], v[150:151], 0, s[0:1]
	global_load_dwordx4 v[4:7], v[12:13], off
	global_load_dwordx4 v[132:135], v[12:13], off offset:128
	s_add_u32 s12, s4, 0x4000
	s_addc_u32 s13, s5, 0
	global_load_dwordx4 v[200:203], v154, s[12:13]
	s_add_u32 s12, s6, 0x2000
	s_addc_u32 s13, s7, 0
	global_load_dwordx4 v[204:207], v196, s[12:13]
	global_load_dwordx4 v[208:211], v[12:13], off offset:256
	v_add_u32_e32 v9, v143, v148
	v_add3_u32 v0, v177, v148, s41
	v_add_u32_e32 v1, v178, v148
	v_add_u32_e32 v8, 0xac00, v0
	v_mov_b32_e32 v159, v97
	s_waitcnt vmcnt(0)
	ds_write_b128 v9, v[188:191]
	ds_write_b128 v186, v[124:127] offset:128
	ds_write2_b64 v0, v[4:5], v[6:7] offset1:1
	ds_write_b128 v1, v[128:131] offset:22016
	ds_write_b128 v186, v[192:195] offset:22144
	ds_write2_b64 v149, v[132:133], v[134:135] offset1:1
	ds_write_b128 v9, v[200:203] offset:44032
	ds_write_b128 v186, v[204:207] offset:44160
	ds_write2_b64 v8, v[208:209], v[210:211] offset1:1
	s_waitcnt lgkmcnt(0)
	s_barrier
	ds_read_b128 v[0:3], v185
	ds_read_b128 v[4:7], v185 offset:32
	s_waitcnt lgkmcnt(1)
	v_mfma_f32_32x32x16_bf16 v[48:63], v[0:3], v[100:103], 0
	s_mov_b32 s4, 0
	s_mov_b32 s5, s4
	s_mov_b32 s6, s4
	s_mov_b32 s7, s4
	s_mov_b32 s8, s4
	s_mov_b32 s9, s4
	s_mov_b32 s10, s4
	s_waitcnt lgkmcnt(0)
	v_mfma_f32_32x32x16_bf16 v[48:63], v[4:7], v[104:107], v[48:63]
	ds_read_b128 v[0:3], v185 offset:64
	ds_read_b128 v[4:7], v185 offset:96
	s_mov_b32 s11, s4
	s_mov_b32 s12, s4
	s_mov_b32 s13, s4
	s_mov_b32 s14, s4
	s_mov_b32 s15, s4
	s_mov_b32 s16, s4
	s_waitcnt lgkmcnt(1)
	v_mfma_f32_32x32x16_bf16 v[48:63], v[0:3], v[108:111], v[48:63]
	s_mov_b32 s17, s4
	s_mov_b32 s18, s4
	s_mov_b32 s19, s4
	s_waitcnt lgkmcnt(0)
	v_mfma_f32_32x32x16_bf16 v[48:63], v[4:7], v[112:115], v[48:63]
	ds_read_b128 v[0:3], v185 offset:128
	ds_read_b128 v[4:7], v185 offset:160
	s_waitcnt lgkmcnt(1)
	v_mfma_f32_32x32x16_bf16 v[48:63], v[0:3], v[116:119], v[48:63]
	s_waitcnt lgkmcnt(0)
	v_mfma_f32_32x32x16_bf16 v[48:63], v[4:7], v[120:123], v[48:63]
	ds_read_b128 v[0:3], v185 offset:6656
	ds_read_b128 v[4:7], v185 offset:6688
	s_waitcnt lgkmcnt(1)
	v_mfma_f32_32x32x16_bf16 v[32:47], v[0:3], v[100:103], 0
	s_waitcnt lgkmcnt(0)
	v_mfma_f32_32x32x16_bf16 v[32:47], v[4:7], v[104:107], v[32:47]
	ds_read_b128 v[0:3], v185 offset:6720
	ds_read_b128 v[4:7], v185 offset:6752
	ds_read_b128 v[16:19], v185 offset:6816
	s_waitcnt lgkmcnt(2)
	v_mfma_f32_32x32x16_bf16 v[32:47], v[0:3], v[108:111], v[32:47]
	ds_read_b128 v[0:3], v185 offset:6784
	s_waitcnt lgkmcnt(2)
	v_mfma_f32_32x32x16_bf16 v[32:47], v[4:7], v[112:115], v[32:47]
	s_waitcnt lgkmcnt(0)
	v_mfma_f32_32x32x16_bf16 v[32:47], v[0:3], v[116:119], v[32:47]
	v_mov_b64_e32 v[0:1], s[4:5]
	v_mov_b64_e32 v[2:3], s[6:7]
	v_mov_b64_e32 v[4:5], s[8:9]
	v_mov_b64_e32 v[6:7], s[10:11]
	v_mov_b64_e32 v[8:9], s[12:13]
	v_mov_b64_e32 v[10:11], s[14:15]
	v_mov_b64_e32 v[12:13], s[16:17]
	v_mfma_f32_32x32x16_bf16 v[32:47], v[16:19], v[120:123], v[32:47]
	v_mov_b64_e32 v[14:15], s[18:19]
	s_nop 15
	s_nop 15
	s_nop 15
	v_mov_b64_e32 v[30:31], v[14:15]
	v_lshl_add_u64 v[98:99], v[152:153], 0, s[34:35]
	v_lshl_add_u64 v[168:169], v[146:147], 0, s[0:1]
	v_lshl_add_u64 v[170:171], v[154:155], 0, s[0:1]
	v_mov_b32_e32 v157, 0
	v_mov_b64_e32 v[28:29], v[12:13]
	v_mov_b64_e32 v[26:27], v[10:11]
	v_mov_b64_e32 v[24:25], v[8:9]
	v_mov_b64_e32 v[22:23], v[6:7]
	v_mov_b64_e32 v[20:21], v[4:5]
	v_mov_b64_e32 v[18:19], v[2:3]
	v_mov_b64_e32 v[16:17], v[0:1]
	v_mov_b32_e32 v96, 0
	v_mov_b32_e32 v228, 0x80000000
	v_mov_b32_e32 v229, v228
	v_mov_b32_e32 v230, v228
	v_mov_b32_e32 v231, v228
	v_mov_b32_e32 v232, v228
	v_mov_b32_e32 v233, v228
	v_mov_b32_e32 v234, v228
	v_mov_b32_e32 v235, v228
	v_mov_b32_e32 v236, v228
	v_mov_b32_e32 v237, v228
	v_mov_b32_e32 v238, v228
	v_mov_b32_e32 v239, v228
	v_mov_b32_e32 v240, v228
	v_mov_b32_e32 v241, v228
	v_mov_b32_e32 v242, v228
	v_mov_b32_e32 v243, v228
	s_add_u32 s48, s37, s0
	s_addc_u32 s49, s38, s1
	s_add_u32 s48, s48, 0x6000
	s_addc_u32 s49, s49, 0
	s_add_u32 s50, s39, s34
	s_addc_u32 s51, s40, s35
	s_add_u32 s50, s50, 0x3000
	s_addc_u32 s51, s51, 0
	s_add_u32 s60, s54, 0x1cd00000
	s_addc_u32 s61, s55, 0
	s_add_u32 s60, s60, s0
	s_addc_u32 s61, s61, s1
	s_add_u32 s60, s60, 0x180
	s_addc_u32 s61, s61, 0
	s_mov_b32 s44, 0
	s_movk_i32 s45, 0x5600
	s_mov_b32 s46, 0xac00
	s_mov_b32 s62, 0x10200
	s_mov_b32 s63, 0x15800
	v_add_u32_e32 v168, v141, v148
	v_add_u32_e32 v169, v174, v175
	v_add3_u32 v170, v176, v148, s41
	v_add3_u32 v171, v182, v136, s41
	v_add3_u32 v172, v183, v136, s41
	v_add_u32_e32 v173, v180, v179
	v_add_u32_e32 v98, v181, v179
	v_and_b32_e32 v99, 0xfff, v152
	v_mov_b32_e32 v212, 0
	v_mov_b32_e32 v213, 0
	v_mov_b32_e32 v214, 0
	v_mov_b32_e32 v215, 0
	v_mov_b32_e32 v216, 0
	v_mov_b32_e32 v217, 0
	v_mov_b32_e32 v218, 0
	v_mov_b32_e32 v219, 0
	v_mov_b32_e32 v220, 0
	v_mov_b32_e32 v221, 0
	v_mov_b32_e32 v222, 0
	v_mov_b32_e32 v223, 0
	global_load_dwordx4 v[128:131], v154, s[48:49]
	global_load_dwordx4 v[124:127], v99, s[50:51]
	global_load_dwordx4 v[132:135], v146, s[60:61]
.LBB0_740:
	s_cmp_eq_u32 s4, 0
	s_cselect_b64 s[76:77], -1, 0
	v_add_u32_e32 v227, s45, v173
	v_add_u32_e32 v245, s45, v98
	ds_read_b128 v[188:191], v227
	ds_read_b128 v[192:195], v245
	ds_read_b128 v[196:199], v227 offset:32
	ds_read_b128 v[200:203], v245 offset:32
	v_mfma_f32_32x32x16_bf16 v[0:15], v[212:215], v[220:223], v[0:15]
	v_add_u32_e32 v246, s44, v171
	v_add_u32_e32 v247, s44, v172
	v_mov_b32_e32 v161, 0
	v_mfma_f32_32x32x16_bf16 v[16:31], v[216:219], v[220:223], v[16:31]
	s_waitcnt lgkmcnt(3)
	v_mfma_f32_32x32x16_bf16 v[80:95], v[188:191], v[100:103], v[228:243]
	ds_read_b128 v[188:191], v227 offset:64
	v_max3_f32 v224, v48, v49, v50
	v_max3_f32 v224, v224, v51, v52
	v_max3_f32 v224, v224, v53, v54
	v_max3_f32 v225, v33, v34, v35
	v_max3_f32 v225, v225, v36, v37
	s_waitcnt lgkmcnt(3)
	v_mfma_f32_32x32x16_bf16 v[64:79], v[192:195], v[100:103], v[228:243]
	ds_read_b128 v[192:195], v245 offset:64
	v_max3_f32 v224, v224, v55, v56
	v_max3_f32 v224, v224, v57, v58
	v_max3_f32 v224, v224, v59, v60
	v_max3_f32 v225, v225, v38, v39
	v_max3_f32 v225, v225, v40, v41
	s_waitcnt lgkmcnt(3)
	v_mfma_f32_32x32x16_bf16 v[80:95], v[196:199], v[104:107], v[80:95]
	ds_read_b128 v[196:199], v227 offset:96
	ds_read2_b64 v[204:207], v246 offset0:0 offset1:2
	ds_read2_b64 v[208:211], v247 offset0:0 offset1:2
	v_max3_f32 v224, v224, v61, v62
	v_max3_f32 v224, v224, v63, v32
	v_max3_f32 v225, v225, v42, v43
	v_max3_f32 v225, v225, v44, v45
	v_max3_f32 v225, v225, v46, v47
	s_waitcnt lgkmcnt(5)
	v_mfma_f32_32x32x16_bf16 v[64:79], v[200:203], v[104:107], v[64:79]
	ds_read_b128 v[200:203], v245 offset:96
	v_max_f32_e32 v224, v224, v225
	v_mov_b32_e32 v226, v224
	v_add_u32_e32 v159, s62, v168
	s_nop 0
	v_permlane32_swap_b32_e32 v224, v226
	v_max_f32_e32 v224, v224, v226
	v_cmp_lt_f32_e32 vcc, s42, v224
	s_or_b64 vcc, s[76:77], vcc
	s_cbranch_vccz .Lattn_e_norare
	s_nop 15
	v_max_f32_e32 v225, v224, v224
	v_max_f32_e32 v225, 0, v225
	v_cndmask_b32_e64 v225, v225, v224, s[76:77]
	v_exp_f32_e64 v226, -v225
	v_add_f32_e32 v96, v96, v225
	v_cndmask_b32_e64 v226, v226, 1.0, s[76:77]
	v_mul_f32_e32 v157, v157, v226
	v_sub_f32_e32 v48, v48, v225
	v_sub_f32_e32 v49, v49, v225
	v_sub_f32_e32 v50, v50, v225
	v_sub_f32_e32 v51, v51, v225
	v_sub_f32_e32 v52, v52, v225
	v_sub_f32_e32 v53, v53, v225
	v_sub_f32_e32 v54, v54, v225
	v_sub_f32_e32 v55, v55, v225
	v_sub_f32_e32 v56, v56, v225
	v_sub_f32_e32 v57, v57, v225
	v_sub_f32_e32 v58, v58, v225
	v_sub_f32_e32 v59, v59, v225
	v_sub_f32_e32 v60, v60, v225
	v_sub_f32_e32 v61, v61, v225
	v_sub_f32_e32 v62, v62, v225
	v_sub_f32_e32 v63, v63, v225
	v_sub_f32_e32 v32, v32, v225
	v_sub_f32_e32 v33, v33, v225
	v_sub_f32_e32 v34, v34, v225
	v_sub_f32_e32 v35, v35, v225
	v_sub_f32_e32 v36, v36, v225
	v_sub_f32_e32 v37, v37, v225
	v_sub_f32_e32 v38, v38, v225
	v_sub_f32_e32 v39, v39, v225
	v_sub_f32_e32 v40, v40, v225
	v_sub_f32_e32 v41, v41, v225
	v_sub_f32_e32 v42, v42, v225
	v_sub_f32_e32 v43, v43, v225
	v_sub_f32_e32 v44, v44, v225
	v_sub_f32_e32 v45, v45, v225
	v_sub_f32_e32 v46, v46, v225
	v_sub_f32_e32 v47, v47, v225
	v_sub_f32_e32 v80, v80, v225
	v_sub_f32_e32 v81, v81, v225
	v_sub_f32_e32 v82, v82, v225
	v_sub_f32_e32 v83, v83, v225
	v_sub_f32_e32 v84, v84, v225
	v_sub_f32_e32 v85, v85, v225
	v_sub_f32_e32 v86, v86, v225
	v_sub_f32_e32 v87, v87, v225
	v_sub_f32_e32 v88, v88, v225
	v_sub_f32_e32 v89, v89, v225
	v_sub_f32_e32 v90, v90, v225
	v_sub_f32_e32 v91, v91, v225
	v_sub_f32_e32 v92, v92, v225
	v_sub_f32_e32 v93, v93, v225
	v_sub_f32_e32 v94, v94, v225
	v_sub_f32_e32 v95, v95, v225
	v_sub_f32_e32 v64, v64, v225
	v_sub_f32_e32 v65, v65, v225
	v_sub_f32_e32 v66, v66, v225
	v_sub_f32_e32 v67, v67, v225
	v_sub_f32_e32 v68, v68, v225
	v_sub_f32_e32 v69, v69, v225
	v_sub_f32_e32 v70, v70, v225
	v_sub_f32_e32 v71, v71, v225
	v_sub_f32_e32 v72, v72, v225
	v_sub_f32_e32 v73, v73, v225
	v_sub_f32_e32 v74, v74, v225
	v_sub_f32_e32 v75, v75, v225
	v_sub_f32_e32 v76, v76, v225
	v_sub_f32_e32 v77, v77, v225
	v_sub_f32_e32 v78, v78, v225
	v_sub_f32_e32 v79, v79, v225
	v_pk_mul_f32 v[0:1], v[0:1], v[226:227] op_sel_hi:[1,0]
	v_pk_mul_f32 v[2:3], v[2:3], v[226:227] op_sel_hi:[1,0]
	v_pk_mul_f32 v[4:5], v[4:5], v[226:227] op_sel_hi:[1,0]
	v_pk_mul_f32 v[6:7], v[6:7], v[226:227] op_sel_hi:[1,0]
	v_pk_mul_f32 v[8:9], v[8:9], v[226:227] op_sel_hi:[1,0]
	v_pk_mul_f32 v[10:11], v[10:11], v[226:227] op_sel_hi:[1,0]
	v_pk_mul_f32 v[12:13], v[12:13], v[226:227] op_sel_hi:[1,0]
	v_pk_mul_f32 v[14:15], v[14:15], v[226:227] op_sel_hi:[1,0]
	v_pk_mul_f32 v[16:17], v[16:17], v[226:227] op_sel_hi:[1,0]
	v_pk_mul_f32 v[18:19], v[18:19], v[226:227] op_sel_hi:[1,0]
	v_pk_mul_f32 v[20:21], v[20:21], v[226:227] op_sel_hi:[1,0]
	v_pk_mul_f32 v[22:23], v[22:23], v[226:227] op_sel_hi:[1,0]
	v_pk_mul_f32 v[24:25], v[24:25], v[226:227] op_sel_hi:[1,0]
	v_pk_mul_f32 v[26:27], v[26:27], v[226:227] op_sel_hi:[1,0]
	v_pk_mul_f32 v[28:29], v[28:29], v[226:227] op_sel_hi:[1,0]
	v_pk_mul_f32 v[30:31], v[30:31], v[226:227] op_sel_hi:[1,0]
	v_xor_b32_e32 v228, 0x80000000, v96
	v_mov_b32_e32 v229, v228
	v_mov_b32_e32 v230, v228
	v_mov_b32_e32 v231, v228
	v_mov_b32_e32 v232, v228
	v_mov_b32_e32 v233, v228
	v_mov_b32_e32 v234, v228
	v_mov_b32_e32 v235, v228
	v_mov_b32_e32 v236, v228
	v_mov_b32_e32 v237, v228
	v_mov_b32_e32 v238, v228
	v_mov_b32_e32 v239, v228
	v_mov_b32_e32 v240, v228
	v_mov_b32_e32 v241, v228
	v_mov_b32_e32 v242, v228
	v_mov_b32_e32 v243, v228
.Lattn_e_norare:
	s_waitcnt lgkmcnt(5)
	v_mfma_f32_32x32x16_bf16 v[80:95], v[188:191], v[108:111], v[80:95]
	ds_read_b128 v[188:191], v227 offset:128
	v_exp_f32_e32 v48, v48
	v_exp_f32_e32 v49, v49
	v_exp_f32_e32 v50, v50
	v_exp_f32_e32 v51, v51
	s_waitcnt lgkmcnt(5)
	v_mfma_f32_32x32x16_bf16 v[64:79], v[192:195], v[108:111], v[64:79]
	v_exp_f32_e32 v52, v52
	v_exp_f32_e32 v53, v53
	v_exp_f32_e32 v54, v54
	v_exp_f32_e32 v55, v55
	s_waitcnt lgkmcnt(4)
	v_mfma_f32_32x32x16_bf16 v[80:95], v[196:199], v[112:115], v[80:95]
	ds_read2_b64 v[212:215], v246 offset0:4 offset1:6
	ds_read2_b64 v[216:219], v247 offset0:4 offset1:6
	v_cvt_pk_bf16_f32 v220, v48, v49
	v_cvt_pk_bf16_f32 v221, v50, v51
	v_cvt_pk_bf16_f32 v222, v52, v53
	v_cvt_pk_bf16_f32 v223, v54, v55
	v_add_f32_e32 v161, v161, v48
	v_add_f32_e32 v161, v161, v49
	v_add_f32_e32 v161, v161, v50
	v_add_f32_e32 v161, v161, v51
	s_waitcnt lgkmcnt(5)
	v_mfma_f32_32x32x16_bf16 v[0:15], v[204:207], v[220:223], v[0:15]
	v_add_f32_e32 v161, v161, v52
	v_add_f32_e32 v161, v161, v53
	v_add_f32_e32 v161, v161, v54
	v_add_f32_e32 v161, v161, v55
	v_exp_f32_e32 v56, v56
	v_exp_f32_e32 v57, v57
	s_waitcnt lgkmcnt(4)
	v_mfma_f32_32x32x16_bf16 v[16:31], v[208:211], v[220:223], v[16:31]
	ds_read_b128 v[192:195], v245 offset:128
	v_exp_f32_e32 v58, v58
	v_exp_f32_e32 v59, v59
	v_exp_f32_e32 v60, v60
	v_exp_f32_e32 v61, v61
	s_waitcnt lgkmcnt(4)
	v_mfma_f32_32x32x16_bf16 v[64:79], v[200:203], v[112:115], v[64:79]
	ds_read_b128 v[196:199], v227 offset:160
	v_exp_f32_e32 v62, v62
	v_exp_f32_e32 v63, v63
	v_cvt_pk_bf16_f32 v220, v56, v57
	v_cvt_pk_bf16_f32 v221, v58, v59
	v_cvt_pk_bf16_f32 v222, v60, v61
	v_cvt_pk_bf16_f32 v223, v62, v63
	s_waitcnt lgkmcnt(4)
	v_mfma_f32_32x32x16_bf16 v[80:95], v[188:191], v[116:119], v[80:95]
	ds_read2_b64 v[204:207], v246 offset0:8 offset1:10
	ds_read2_b64 v[208:211], v247 offset0:8 offset1:10
	v_add_f32_e32 v161, v161, v56
	v_add_f32_e32 v161, v161, v57
	v_add_f32_e32 v161, v161, v58
	v_add_f32_e32 v161, v161, v59
	v_add_f32_e32 v161, v161, v60
	v_add_f32_e32 v161, v161, v61
	v_add_f32_e32 v161, v161, v62
	v_add_f32_e32 v161, v161, v63
	s_waitcnt lgkmcnt(5)
	v_mfma_f32_32x32x16_bf16 v[0:15], v[212:215], v[220:223], v[0:15]
	v_exp_f32_e32 v32, v32
	v_exp_f32_e32 v33, v33
	v_exp_f32_e32 v34, v34
	v_exp_f32_e32 v35, v35
	s_waitcnt lgkmcnt(4)
	v_mfma_f32_32x32x16_bf16 v[16:31], v[216:219], v[220:223], v[16:31]
	ds_read_b128 v[200:203], v245 offset:160
	s_waitcnt vmcnt(0)
	ds_write_b128 v159, v[128:131]
	v_add_u32_e32 v159, s62, v169
	ds_write_b128 v159, v[124:127] offset:128
	v_add_u32_e32 v159, s62, v170
	ds_write2_b64 v159, v[132:133], v[134:135] offset1:1
	v_exp_f32_e32 v36, v36
	v_exp_f32_e32 v37, v37
	v_exp_f32_e32 v38, v38
	v_exp_f32_e32 v39, v39
	s_waitcnt lgkmcnt(7)
	v_mfma_f32_32x32x16_bf16 v[64:79], v[192:195], v[116:119], v[64:79]
	ds_read2_b64 v[212:215], v246 offset0:12 offset1:14
	ds_read2_b64 v[216:219], v247 offset0:12 offset1:14
	s_cmpk_gt_u32 s4, 0x3f
	s_cbranch_scc1 .Lattn_e_nopf
	s_add_u32 s48, s48, 0x2000
	s_addc_u32 s49, s49, 0
	s_add_u32 s50, s50, 0x1000
	s_addc_u32 s51, s51, 0
	s_add_u32 s60, s60, 0x80
	s_addc_u32 s61, s61, 0
	global_load_dwordx4 v[128:131], v154, s[48:49]
	global_load_dwordx4 v[124:127], v99, s[50:51]
	global_load_dwordx4 v[132:135], v146, s[60:61]
.Lattn_e_nopf:
	v_cvt_pk_bf16_f32 v220, v32, v33
	v_cvt_pk_bf16_f32 v221, v34, v35
	v_cvt_pk_bf16_f32 v222, v36, v37
	v_cvt_pk_bf16_f32 v223, v38, v39
	v_add_f32_e32 v161, v161, v32
	v_add_f32_e32 v161, v161, v33
	v_add_f32_e32 v161, v161, v34
	v_add_f32_e32 v161, v161, v35
	s_waitcnt lgkmcnt(8)
	v_mfma_f32_32x32x16_bf16 v[80:95], v[196:199], v[120:123], v[80:95]
	v_add_f32_e32 v161, v161, v36
	v_add_f32_e32 v161, v161, v37
	v_add_f32_e32 v161, v161, v38
	v_add_f32_e32 v161, v161, v39
	v_exp_f32_e32 v40, v40
	v_exp_f32_e32 v41, v41
	s_waitcnt lgkmcnt(7)
	v_mfma_f32_32x32x16_bf16 v[0:15], v[204:207], v[220:223], v[0:15]
	v_exp_f32_e32 v42, v42
	v_exp_f32_e32 v43, v43
	v_exp_f32_e32 v44, v44
	v_exp_f32_e32 v45, v45
	s_waitcnt lgkmcnt(6)
	v_mfma_f32_32x32x16_bf16 v[16:31], v[208:211], v[220:223], v[16:31]
	v_exp_f32_e32 v46, v46
	v_exp_f32_e32 v47, v47
	v_cvt_pk_bf16_f32 v220, v40, v41
	v_cvt_pk_bf16_f32 v221, v42, v43
	v_cvt_pk_bf16_f32 v222, v44, v45
	v_cvt_pk_bf16_f32 v223, v46, v47
	s_waitcnt lgkmcnt(5)
	v_mfma_f32_32x32x16_bf16 v[64:79], v[200:203], v[120:123], v[64:79]
	v_add_f32_e32 v161, v161, v40
	v_add_f32_e32 v161, v161, v41
	v_add_f32_e32 v161, v161, v42
	v_add_f32_e32 v161, v161, v43
	v_add_f32_e32 v161, v161, v44
	v_add_f32_e32 v161, v161, v45
	v_add_f32_e32 v161, v161, v46
	v_add_f32_e32 v161, v161, v47
	s_mov_b32 s47, s44
	s_mov_b32 s44, s45
	s_mov_b32 s45, s46
	s_mov_b32 s46, s62
	s_mov_b32 s62, s63
	s_mov_b32 s63, s47
	v_add_f32_e32 v157, v157, v161
	s_waitcnt lgkmcnt(0)
	v_add_u32_e32 v227, s45, v173
	v_add_u32_e32 v245, s45, v98
	ds_read_b128 v[188:191], v227
	ds_read_b128 v[192:195], v245
	ds_read_b128 v[196:199], v227 offset:32
	ds_read_b128 v[200:203], v245 offset:32
	v_mfma_f32_32x32x16_bf16 v[0:15], v[212:215], v[220:223], v[0:15]
	v_add_u32_e32 v246, s44, v171
	v_add_u32_e32 v247, s44, v172
	v_mov_b32_e32 v161, 0
	v_mfma_f32_32x32x16_bf16 v[16:31], v[216:219], v[220:223], v[16:31]
	s_waitcnt lgkmcnt(3)
	v_mfma_f32_32x32x16_bf16 v[48:63], v[188:191], v[100:103], v[228:243]
	ds_read_b128 v[188:191], v227 offset:64
	v_max3_f32 v224, v80, v81, v82
	v_max3_f32 v224, v224, v83, v84
	v_max3_f32 v224, v224, v85, v86
	v_max3_f32 v225, v65, v66, v67
	v_max3_f32 v225, v225, v68, v69
	s_waitcnt lgkmcnt(3)
	v_mfma_f32_32x32x16_bf16 v[32:47], v[192:195], v[100:103], v[228:243]
	ds_read_b128 v[192:195], v245 offset:64
	v_max3_f32 v224, v224, v87, v88
	v_max3_f32 v224, v224, v89, v90
	v_max3_f32 v224, v224, v91, v92
	v_max3_f32 v225, v225, v70, v71
	v_max3_f32 v225, v225, v72, v73
	s_waitcnt lgkmcnt(3)
	v_mfma_f32_32x32x16_bf16 v[48:63], v[196:199], v[104:107], v[48:63]
	ds_read_b128 v[196:199], v227 offset:96
	ds_read2_b64 v[204:207], v246 offset0:0 offset1:2
	ds_read2_b64 v[208:211], v247 offset0:0 offset1:2
	v_max3_f32 v224, v224, v93, v94
	v_max3_f32 v224, v224, v95, v64
	v_max3_f32 v225, v225, v74, v75
	v_max3_f32 v225, v225, v76, v77
	v_max3_f32 v225, v225, v78, v79
	s_waitcnt lgkmcnt(5)
	v_mfma_f32_32x32x16_bf16 v[32:47], v[200:203], v[104:107], v[32:47]
	ds_read_b128 v[200:203], v245 offset:96
	v_max_f32_e32 v224, v224, v225
	v_mov_b32_e32 v226, v224
	v_add_u32_e32 v159, s62, v168
	s_nop 0
	v_permlane32_swap_b32_e32 v224, v226
	v_max_f32_e32 v224, v224, v226
	v_cmp_lt_f32_e32 vcc, s42, v224
	s_cbranch_vccz .Lattn_o_norare
	s_nop 15
	v_max_f32_e32 v225, v224, v224
	v_max_f32_e32 v225, 0, v225
	v_exp_f32_e64 v226, -v225
	v_add_f32_e32 v96, v96, v225
	s_nop 0
	v_mul_f32_e32 v157, v157, v226
	v_sub_f32_e32 v80, v80, v225
	v_sub_f32_e32 v81, v81, v225
	v_sub_f32_e32 v82, v82, v225
	v_sub_f32_e32 v83, v83, v225
	v_sub_f32_e32 v84, v84, v225
	v_sub_f32_e32 v85, v85, v225
	v_sub_f32_e32 v86, v86, v225
	v_sub_f32_e32 v87, v87, v225
	v_sub_f32_e32 v88, v88, v225
	v_sub_f32_e32 v89, v89, v225
	v_sub_f32_e32 v90, v90, v225
	v_sub_f32_e32 v91, v91, v225
	v_sub_f32_e32 v92, v92, v225
	v_sub_f32_e32 v93, v93, v225
	v_sub_f32_e32 v94, v94, v225
	v_sub_f32_e32 v95, v95, v225
	v_sub_f32_e32 v64, v64, v225
	v_sub_f32_e32 v65, v65, v225
	v_sub_f32_e32 v66, v66, v225
	v_sub_f32_e32 v67, v67, v225
	v_sub_f32_e32 v68, v68, v225
	v_sub_f32_e32 v69, v69, v225
	v_sub_f32_e32 v70, v70, v225
	v_sub_f32_e32 v71, v71, v225
	v_sub_f32_e32 v72, v72, v225
	v_sub_f32_e32 v73, v73, v225
	v_sub_f32_e32 v74, v74, v225
	v_sub_f32_e32 v75, v75, v225
	v_sub_f32_e32 v76, v76, v225
	v_sub_f32_e32 v77, v77, v225
	v_sub_f32_e32 v78, v78, v225
	v_sub_f32_e32 v79, v79, v225
	v_sub_f32_e32 v48, v48, v225
	v_sub_f32_e32 v49, v49, v225
	v_sub_f32_e32 v50, v50, v225
	v_sub_f32_e32 v51, v51, v225
	v_sub_f32_e32 v52, v52, v225
	v_sub_f32_e32 v53, v53, v225
	v_sub_f32_e32 v54, v54, v225
	v_sub_f32_e32 v55, v55, v225
	v_sub_f32_e32 v56, v56, v225
	v_sub_f32_e32 v57, v57, v225
	v_sub_f32_e32 v58, v58, v225
	v_sub_f32_e32 v59, v59, v225
	v_sub_f32_e32 v60, v60, v225
	v_sub_f32_e32 v61, v61, v225
	v_sub_f32_e32 v62, v62, v225
	v_sub_f32_e32 v63, v63, v225
	v_sub_f32_e32 v32, v32, v225
	v_sub_f32_e32 v33, v33, v225
	v_sub_f32_e32 v34, v34, v225
	v_sub_f32_e32 v35, v35, v225
	v_sub_f32_e32 v36, v36, v225
	v_sub_f32_e32 v37, v37, v225
	v_sub_f32_e32 v38, v38, v225
	v_sub_f32_e32 v39, v39, v225
	v_sub_f32_e32 v40, v40, v225
	v_sub_f32_e32 v41, v41, v225
	v_sub_f32_e32 v42, v42, v225
	v_sub_f32_e32 v43, v43, v225
	v_sub_f32_e32 v44, v44, v225
	v_sub_f32_e32 v45, v45, v225
	v_sub_f32_e32 v46, v46, v225
	v_sub_f32_e32 v47, v47, v225
	v_pk_mul_f32 v[0:1], v[0:1], v[226:227] op_sel_hi:[1,0]
	v_pk_mul_f32 v[2:3], v[2:3], v[226:227] op_sel_hi:[1,0]
	v_pk_mul_f32 v[4:5], v[4:5], v[226:227] op_sel_hi:[1,0]
	v_pk_mul_f32 v[6:7], v[6:7], v[226:227] op_sel_hi:[1,0]
	v_pk_mul_f32 v[8:9], v[8:9], v[226:227] op_sel_hi:[1,0]
	v_pk_mul_f32 v[10:11], v[10:11], v[226:227] op_sel_hi:[1,0]
	v_pk_mul_f32 v[12:13], v[12:13], v[226:227] op_sel_hi:[1,0]
	v_pk_mul_f32 v[14:15], v[14:15], v[226:227] op_sel_hi:[1,0]
	v_pk_mul_f32 v[16:17], v[16:17], v[226:227] op_sel_hi:[1,0]
	v_pk_mul_f32 v[18:19], v[18:19], v[226:227] op_sel_hi:[1,0]
	v_pk_mul_f32 v[20:21], v[20:21], v[226:227] op_sel_hi:[1,0]
	v_pk_mul_f32 v[22:23], v[22:23], v[226:227] op_sel_hi:[1,0]
	v_pk_mul_f32 v[24:25], v[24:25], v[226:227] op_sel_hi:[1,0]
	v_pk_mul_f32 v[26:27], v[26:27], v[226:227] op_sel_hi:[1,0]
	v_pk_mul_f32 v[28:29], v[28:29], v[226:227] op_sel_hi:[1,0]
	v_pk_mul_f32 v[30:31], v[30:31], v[226:227] op_sel_hi:[1,0]
	v_xor_b32_e32 v228, 0x80000000, v96
	v_mov_b32_e32 v229, v228
	v_mov_b32_e32 v230, v228
	v_mov_b32_e32 v231, v228
	v_mov_b32_e32 v232, v228
	v_mov_b32_e32 v233, v228
	v_mov_b32_e32 v234, v228
	v_mov_b32_e32 v235, v228
	v_mov_b32_e32 v236, v228
	v_mov_b32_e32 v237, v228
	v_mov_b32_e32 v238, v228
	v_mov_b32_e32 v239, v228
	v_mov_b32_e32 v240, v228
	v_mov_b32_e32 v241, v228
	v_mov_b32_e32 v242, v228
	v_mov_b32_e32 v243, v228
.Lattn_o_norare:
	s_waitcnt lgkmcnt(5)
	v_mfma_f32_32x32x16_bf16 v[48:63], v[188:191], v[108:111], v[48:63]
	ds_read_b128 v[188:191], v227 offset:128
	v_exp_f32_e32 v80, v80
	v_exp_f32_e32 v81, v81
	v_exp_f32_e32 v82, v82
	v_exp_f32_e32 v83, v83
	s_waitcnt lgkmcnt(5)
	v_mfma_f32_32x32x16_bf16 v[32:47], v[192:195], v[108:111], v[32:47]
	v_exp_f32_e32 v84, v84
	v_exp_f32_e32 v85, v85
	v_exp_f32_e32 v86, v86
	v_exp_f32_e32 v87, v87
	s_waitcnt lgkmcnt(4)
	v_mfma_f32_32x32x16_bf16 v[48:63], v[196:199], v[112:115], v[48:63]
	ds_read2_b64 v[212:215], v246 offset0:4 offset1:6
	ds_read2_b64 v[216:219], v247 offset0:4 offset1:6
	v_cvt_pk_bf16_f32 v220, v80, v81
	v_cvt_pk_bf16_f32 v221, v82, v83
	v_cvt_pk_bf16_f32 v222, v84, v85
	v_cvt_pk_bf16_f32 v223, v86, v87
	v_add_f32_e32 v161, v161, v80
	v_add_f32_e32 v161, v161, v81
	v_add_f32_e32 v161, v161, v82
	v_add_f32_e32 v161, v161, v83
	s_waitcnt lgkmcnt(5)
	v_mfma_f32_32x32x16_bf16 v[0:15], v[204:207], v[220:223], v[0:15]
	v_add_f32_e32 v161, v161, v84
	v_add_f32_e32 v161, v161, v85
	v_add_f32_e32 v161, v161, v86
	v_add_f32_e32 v161, v161, v87
	v_exp_f32_e32 v88, v88
	v_exp_f32_e32 v89, v89
	s_waitcnt lgkmcnt(4)
	v_mfma_f32_32x32x16_bf16 v[16:31], v[208:211], v[220:223], v[16:31]
	ds_read_b128 v[192:195], v245 offset:128
	v_exp_f32_e32 v90, v90
	v_exp_f32_e32 v91, v91
	v_exp_f32_e32 v92, v92
	v_exp_f32_e32 v93, v93
	s_waitcnt lgkmcnt(4)
	v_mfma_f32_32x32x16_bf16 v[32:47], v[200:203], v[112:115], v[32:47]
	ds_read_b128 v[196:199], v227 offset:160
	v_exp_f32_e32 v94, v94
	v_exp_f32_e32 v95, v95
	v_cvt_pk_bf16_f32 v220, v88, v89
	v_cvt_pk_bf16_f32 v221, v90, v91
	v_cvt_pk_bf16_f32 v222, v92, v93
	v_cvt_pk_bf16_f32 v223, v94, v95
	s_waitcnt lgkmcnt(4)
	v_mfma_f32_32x32x16_bf16 v[48:63], v[188:191], v[116:119], v[48:63]
	ds_read2_b64 v[204:207], v246 offset0:8 offset1:10
	ds_read2_b64 v[208:211], v247 offset0:8 offset1:10
	v_add_f32_e32 v161, v161, v88
	v_add_f32_e32 v161, v161, v89
	v_add_f32_e32 v161, v161, v90
	v_add_f32_e32 v161, v161, v91
	v_add_f32_e32 v161, v161, v92
	v_add_f32_e32 v161, v161, v93
	v_add_f32_e32 v161, v161, v94
	v_add_f32_e32 v161, v161, v95
	s_waitcnt lgkmcnt(5)
	v_mfma_f32_32x32x16_bf16 v[0:15], v[212:215], v[220:223], v[0:15]
	v_exp_f32_e32 v64, v64
	v_exp_f32_e32 v65, v65
	v_exp_f32_e32 v66, v66
	v_exp_f32_e32 v67, v67
	s_waitcnt lgkmcnt(4)
	v_mfma_f32_32x32x16_bf16 v[16:31], v[216:219], v[220:223], v[16:31]
	ds_read_b128 v[200:203], v245 offset:160
	s_waitcnt vmcnt(0)
	ds_write_b128 v159, v[128:131]
	v_add_u32_e32 v159, s62, v169
	ds_write_b128 v159, v[124:127] offset:128
	v_add_u32_e32 v159, s62, v170
	ds_write2_b64 v159, v[132:133], v[134:135] offset1:1
	v_exp_f32_e32 v68, v68
	v_exp_f32_e32 v69, v69
	v_exp_f32_e32 v70, v70
	v_exp_f32_e32 v71, v71
	s_waitcnt lgkmcnt(7)
	v_mfma_f32_32x32x16_bf16 v[32:47], v[192:195], v[116:119], v[32:47]
	ds_read2_b64 v[212:215], v246 offset0:12 offset1:14
	ds_read2_b64 v[216:219], v247 offset0:12 offset1:14
	s_cmpk_gt_u32 s4, 0x3e
	s_cbranch_scc1 .Lattn_o_nopf
	s_add_u32 s48, s48, 0x2000
	s_addc_u32 s49, s49, 0
	s_add_u32 s50, s50, 0x1000
	s_addc_u32 s51, s51, 0
	s_add_u32 s60, s60, 0x80
	s_addc_u32 s61, s61, 0
	global_load_dwordx4 v[128:131], v154, s[48:49]
	global_load_dwordx4 v[124:127], v99, s[50:51]
	global_load_dwordx4 v[132:135], v146, s[60:61]
.Lattn_o_nopf:
	v_cvt_pk_bf16_f32 v220, v64, v65
	v_cvt_pk_bf16_f32 v221, v66, v67
	v_cvt_pk_bf16_f32 v222, v68, v69
	v_cvt_pk_bf16_f32 v223, v70, v71
	v_add_f32_e32 v161, v161, v64
	v_add_f32_e32 v161, v161, v65
	v_add_f32_e32 v161, v161, v66
	v_add_f32_e32 v161, v161, v67
	s_waitcnt lgkmcnt(8)
	v_mfma_f32_32x32x16_bf16 v[48:63], v[196:199], v[120:123], v[48:63]
	v_add_f32_e32 v161, v161, v68
	v_add_f32_e32 v161, v161, v69
	v_add_f32_e32 v161, v161, v70
	v_add_f32_e32 v161, v161, v71
	v_exp_f32_e32 v72, v72
	v_exp_f32_e32 v73, v73
	s_waitcnt lgkmcnt(7)
	v_mfma_f32_32x32x16_bf16 v[0:15], v[204:207], v[220:223], v[0:15]
	v_exp_f32_e32 v74, v74
	v_exp_f32_e32 v75, v75
	v_exp_f32_e32 v76, v76
	v_exp_f32_e32 v77, v77
	s_waitcnt lgkmcnt(6)
	v_mfma_f32_32x32x16_bf16 v[16:31], v[208:211], v[220:223], v[16:31]
	v_exp_f32_e32 v78, v78
	v_exp_f32_e32 v79, v79
	v_cvt_pk_bf16_f32 v220, v72, v73
	v_cvt_pk_bf16_f32 v221, v74, v75
	v_cvt_pk_bf16_f32 v222, v76, v77
	v_cvt_pk_bf16_f32 v223, v78, v79
	s_waitcnt lgkmcnt(5)
	v_mfma_f32_32x32x16_bf16 v[32:47], v[200:203], v[120:123], v[32:47]
	v_add_f32_e32 v161, v161, v72
	v_add_f32_e32 v161, v161, v73
	v_add_f32_e32 v161, v161, v74
	v_add_f32_e32 v161, v161, v75
	v_add_f32_e32 v161, v161, v76
	v_add_f32_e32 v161, v161, v77
	v_add_f32_e32 v161, v161, v78
	v_add_f32_e32 v161, v161, v79
	s_mov_b32 s47, s44
	s_mov_b32 s44, s45
	s_mov_b32 s45, s46
	s_mov_b32 s46, s62
	s_mov_b32 s62, s63
	s_mov_b32 s63, s47
	v_add_f32_e32 v157, v157, v161
	s_waitcnt lgkmcnt(0)
	s_barrier
	s_add_i32 s4, s4, 2
	s_cmpk_lt_u32 s4, 0x44
	s_cbranch_scc1 .LBB0_740
	v_mfma_f32_32x32x16_bf16 v[0:15], v[212:215], v[220:223], v[0:15]
	v_mfma_f32_32x32x16_bf16 v[16:31], v[216:219], v[220:223], v[16:31]
	s_nop 7
	s_branch .LBB0_730
